# split-update version + helper derive in a single pass (all raw reads up front, no intermediate LDS drains)
# speedup vs baseline: 1.0071x; 1.0071x over previous
.Lmy_f_nol34:
	s_waitcnt lgkmcnt(0)
	s_bfe_u32 s96, s62, 0x20006
	s_lshl_b32 s100, s96, 11
	v_lshl_add_u32 v72, v224, 2, s100
	s_and_b32 s97, s96, 1
	s_mul_i32 s97, s97, 0x2700
	s_mov_b32 s101, 0x1c000
	s_mov_b32 s100, 0x6100
	s_bitcmp0_b32 s65, 0
	s_cselect_b32 s101, 0xe000, s101
	s_cselect_b32 s100, 0x4e00, s100
	s_cmp_gt_u32 s96, 1
	s_cselect_b32 s100, s100, 0
	s_add_i32 s97, s97, s101
	s_add_i32 s97, s97, s100
	ds_read_b32 v80, v72
	ds_read_b32 v81, v72 offset:256
	ds_read_b32 v82, v72 offset:512
	ds_read_b32 v83, v72 offset:768
	ds_read_b32 v84, v72 offset:1024
	ds_read_b32 v85, v72 offset:1280
	ds_read_b32 v86, v72 offset:1536
	ds_read_b32 v87, v72 offset:1792
	ds_read_b32 v88, v72 offset:8192
	ds_read_b32 v89, v72 offset:8448
	ds_read_b32 v90, v72 offset:8704
	ds_read_b32 v91, v72 offset:8960
	ds_read_b32 v92, v72 offset:9216
	ds_read_b32 v93, v72 offset:9472
	ds_read_b32 v94, v72 offset:9728
	ds_read_b32 v95, v72 offset:9984
	ds_read_b32 v96, v72 offset:32768
	ds_read_b32 v97, v72 offset:33024
	ds_read_b32 v98, v72 offset:33280
	ds_read_b32 v99, v72 offset:33536
	ds_read_b32 v100, v72 offset:33792
	ds_read_b32 v101, v72 offset:34048
	ds_read_b32 v102, v72 offset:34304
	ds_read_b32 v103, v72 offset:34560
	ds_read_b32 v180, v72 offset:16384
	ds_read_b32 v181, v72 offset:16640
	ds_read_b32 v182, v72 offset:16896
	ds_read_b32 v183, v72 offset:17152
	ds_read_b32 v184, v72 offset:17408
	ds_read_b32 v185, v72 offset:17664
	ds_read_b32 v186, v72 offset:17920
	ds_read_b32 v187, v72 offset:18176
	ds_read_b32 v188, v72 offset:24576
	ds_read_b32 v189, v72 offset:24832
	ds_read_b32 v190, v72 offset:25088
	ds_read_b32 v191, v72 offset:25344
	ds_read_b32 v192, v72 offset:25600
	ds_read_b32 v193, v72 offset:25856
	ds_read_b32 v194, v72 offset:26112
	ds_read_b32 v195, v72 offset:26368
	v_and_b32_e32 v74, 3, v224
	v_bfe_u32 v75, v224, 2, 2
	v_lshrrev_b32_e32 v76, 4, v224
	v_lshlrev_b32_e32 v74, 2, v74
	v_lshl_add_u32 v74, v75, 8, v74
	v_lshl_add_u32 v74, v76, 10, v74
	s_add_i32 s100, s97, 0x0
	v_add_u32_e32 v74, s100, v74
	v_and_b32_e32 v196, 15, v224
	v_lshlrev_b32_e32 v196, 4, v196
	v_lshl_add_u32 v196, v76, 10, v196
	s_add_i32 s101, s97, 0x1000
	v_add_u32_e32 v196, s101, v196
	s_add_i32 s101, s97, 0x2000
	v_lshl_add_u32 v197, v224, 2, s101
	v_xor_b32_e32 v76, 0, v75
	v_xor_b32_e32 v77, 1, v75
	v_xor_b32_e32 v78, 2, v75
	v_xor_b32_e32 v79, 3, v75
	v_lshl_add_u32 v76, v76, 4, v74
	v_lshl_add_u32 v77, v77, 4, v74
	v_lshl_add_u32 v78, v78, 4, v74
	v_lshl_add_u32 v79, v79, 4, v74
	s_waitcnt lgkmcnt(15)
	v_mov_b32_e32 v104, v80
	v_mul_f32_e32 v105, v104, v81
	v_mul_f32_e32 v106, v105, v82
	v_mul_f32_e32 v107, v106, v83
	v_mul_f32_e32 v108, v107, v84
	v_mul_f32_e32 v109, v108, v85
	v_mul_f32_e32 v110, v109, v86
	v_mul_f32_e32 v111, v110, v87
	v_rcp_f32_e32 v216, v104
	v_rcp_f32_e32 v217, v105
	v_rcp_f32_e32 v218, v106
	v_rcp_f32_e32 v219, v107
	v_rcp_f32_e32 v220, v108
	v_rcp_f32_e32 v221, v109
	v_rcp_f32_e32 v222, v110
	v_rcp_f32_e32 v223, v111
	v_mov_b32_e32 v112, v88
	v_mul_f32_e32 v113, v104, v89
	v_mul_f32_e32 v114, v105, v90
	v_mul_f32_e32 v115, v106, v91
	v_mul_f32_e32 v116, v107, v92
	v_mul_f32_e32 v117, v108, v93
	v_mul_f32_e32 v118, v109, v94
	v_mul_f32_e32 v119, v110, v95
	v_mul_f32_e32 v120, v104, v96
	v_mul_f32_e32 v121, v105, v97
	v_mul_f32_e32 v122, v106, v98
	v_mul_f32_e32 v123, v107, v99
	v_mul_f32_e32 v124, v108, v100
	v_mul_f32_e32 v125, v109, v101
	v_mul_f32_e32 v126, v110, v102
	v_mul_f32_e32 v127, v111, v103
	ds_write_b32 v76, v112
	ds_write_b32 v77, v113
	ds_write_b32 v78, v114
	ds_write_b32 v79, v115
	ds_write_b32 v76, v116 offset:64
	ds_write_b32 v77, v117 offset:64
	ds_write_b32 v78, v118 offset:64
	ds_write_b32 v79, v119 offset:64
	ds_write_b32 v76, v120 offset:128
	ds_write_b32 v77, v121 offset:128
	ds_write_b32 v78, v122 offset:128
	ds_write_b32 v79, v123 offset:128
	ds_write_b32 v76, v124 offset:192
	ds_write_b32 v77, v125 offset:192
	ds_write_b32 v78, v126 offset:192
	ds_write_b32 v79, v127 offset:192
	s_waitcnt lgkmcnt(15)
	v_mul_f32_e32 v208, v216, v188
	v_mul_f32_e32 v209, v217, v189
	v_mul_f32_e32 v210, v218, v190
	v_mul_f32_e32 v211, v219, v191
	v_mul_f32_e32 v212, v220, v192
	v_mul_f32_e32 v213, v221, v193
	v_mul_f32_e32 v214, v222, v194
	v_mul_f32_e32 v215, v223, v195
	v_mul_f32_e32 v200, v216, v180
	v_mul_f32_e32 v201, v217, v181
	v_mul_f32_e32 v202, v218, v182
	v_mul_f32_e32 v203, v219, v183
	v_mul_f32_e32 v204, v220, v184
	v_mul_f32_e32 v205, v221, v185
	v_mul_f32_e32 v206, v222, v186
	v_mul_f32_e32 v207, v223, v187
	ds_write_b128 v196, v[200:203]
	ds_write_b128 v196, v[204:207] offset:256
	ds_write_b128 v196, v[208:211] offset:512
	ds_write_b128 v196, v[212:215] offset:768
	ds_write_b32 v197, v111
	s_bfe_u32 s96, s62, 0x20006
	s_and_b32 s97, s96, 1
	s_mul_i32 s97, s97, 0x2700
	s_mov_b32 s101, 0x1c000
	s_mov_b32 s100, 0x6100
	s_bitcmp0_b32 s65, 0
	s_cselect_b32 s101, 0xe000, s101
	s_cselect_b32 s100, 0x4e00, s100
	s_cmp_gt_u32 s96, 1
	s_cselect_b32 s100, s100, 0
	s_add_i32 s97, s97, s101
	s_add_i32 s97, s97, s100
	s_mov_b32 s96, s97
	v_and_b32_e32 v72, 3, v233
	v_lshrrev_b32_e32 v73, 2, v233
	v_lshlrev_b32_e32 v72, 2, v72
	v_lshl_add_u32 v72, v73, 8, v72
	v_lshl_add_u32 v72, v234, 6, v72
	s_add_i32 s97, s96, 0x1000
	v_add_u32_e32 v78, s97, v72
	v_xor_b32_e32 v79, v224, v234
	v_lshl_add_u32 v79, v79, 4, s96
	ds_read_b128 v[96:99], v79
	ds_read_b128 v[100:103], v79 offset:1024
	ds_read_b128 v[104:107], v79 offset:2048
	ds_read_b128 v[108:111], v79 offset:3072
	ds_read_b32 v80, v78
	ds_read_b32 v81, v78 offset:16
	ds_read_b32 v82, v78 offset:32
	ds_read_b32 v83, v78 offset:48
	ds_read_b32 v84, v78 offset:1024
	ds_read_b32 v85, v78 offset:1040
	ds_read_b32 v86, v78 offset:1056
	ds_read_b32 v87, v78 offset:1072
	ds_read_b32 v88, v78 offset:2048
	ds_read_b32 v89, v78 offset:2064
	ds_read_b32 v90, v78 offset:2080
	ds_read_b32 v91, v78 offset:2096
	ds_read_b32 v92, v78 offset:3072
	ds_read_b32 v93, v78 offset:3088
	ds_read_b32 v94, v78 offset:3104
	ds_read_b32 v95, v78 offset:3120
	v_lshl_add_u32 v74, v224, 2, s96
	ds_write_b32 v74, v235 offset:9728
	v_add_u32_e32 v75, -1, v233
	v_mov_b32_e32 v76, -1
	v_cndmask_b32_e64 v75, v76, v75, s[98:99]
	v_cmp_lt_u32_e64 s[100:101], 7, v233
	v_add_u32_e32 v76, -8, v233
	v_and_b32_e32 v77, 1, v234
	v_cndmask_b32_e64 v75, v75, v76, s[100:101]
	v_lshlrev_b32_e32 v77, 2, v77
	v_sub_u32_e32 v76, v75, v77
	v_lshlrev_b32_e32 v77, 2, v234
	v_sub_u32_e32 v77, v233, v77
	v_add_u32_e32 v77, -1, v77
	s_waitcnt lgkmcnt(15)
	v_mfma_f32_16x16x4_f32 v[244:247], v80, v96, 0
	v_mfma_f32_16x16x4_f32 v[240:243], v81, v97, 0
	s_waitcnt lgkmcnt(14)
	v_mfma_f32_16x16x4_f32 v[244:247], v82, v98, v[244:247]
	s_waitcnt lgkmcnt(13)
	v_mfma_f32_16x16x4_f32 v[240:243], v83, v99, v[240:243]
	s_waitcnt lgkmcnt(12)
	v_mfma_f32_16x16x4_f32 v[244:247], v84, v100, v[244:247]
	s_waitcnt lgkmcnt(11)
	v_mfma_f32_16x16x4_f32 v[240:243], v85, v101, v[240:243]
	s_waitcnt lgkmcnt(10)
	v_mfma_f32_16x16x4_f32 v[244:247], v86, v102, v[244:247]
	s_waitcnt lgkmcnt(9)
	v_mfma_f32_16x16x4_f32 v[240:243], v87, v103, v[240:243]
	s_waitcnt lgkmcnt(8)
	v_mfma_f32_16x16x4_f32 v[244:247], v88, v104, v[244:247]
	s_waitcnt lgkmcnt(7)
	v_mfma_f32_16x16x4_f32 v[240:243], v89, v105, v[240:243]
	s_waitcnt lgkmcnt(6)
	v_mfma_f32_16x16x4_f32 v[244:247], v90, v106, v[244:247]
	s_waitcnt lgkmcnt(5)
	v_mfma_f32_16x16x4_f32 v[240:243], v91, v107, v[240:243]
	s_waitcnt lgkmcnt(4)
	v_mfma_f32_16x16x4_f32 v[244:247], v92, v108, v[244:247]
	s_waitcnt lgkmcnt(3)
	v_mfma_f32_16x16x4_f32 v[240:243], v93, v109, v[240:243]
	s_waitcnt lgkmcnt(2)
	v_mfma_f32_16x16x4_f32 v[244:247], v94, v110, v[244:247]
	s_waitcnt lgkmcnt(1)
	v_mfma_f32_16x16x4_f32 v[240:243], v95, v111, v[240:243]
	s_nop 9
	v_add_f32_e32 v244, v244, v240
	v_add_f32_e32 v245, v245, v241
	v_add_f32_e32 v246, v246, v242
	v_add_f32_e32 v247, v247, v243
	v_cmp_le_i32_e64 s[96:97], 0, v76
	v_cmp_le_i32_e64 s[100:101], 1, v76
	s_nop 0
	v_cndmask_b32_e64 v128, 0, v244, s[96:97]
	v_cndmask_b32_e64 v129, 0, v245, s[100:101]
	v_cmp_le_i32_e64 s[96:97], 2, v76
	v_cmp_le_i32_e64 s[100:101], 3, v76
	s_nop 0
	v_cndmask_b32_e64 v130, 0, v246, s[96:97]
	v_cndmask_b32_e64 v131, 0, v247, s[100:101]
	s_bfe_u32 s96, s62, 0x20006
	s_and_b32 s97, s96, 1
	s_mul_i32 s97, s97, 0x2700
	s_mov_b32 s101, 0x1c000
	s_mov_b32 s100, 0x6100
	s_bitcmp0_b32 s65, 0
	s_cselect_b32 s101, 0xe000, s101
	s_cselect_b32 s100, 0x4e00, s100
	s_cmp_gt_u32 s96, 1
	s_cselect_b32 s100, s100, 0
	s_add_i32 s97, s97, s101
	s_add_i32 s97, s97, s100
	v_xor_b32_e32 v74, v224, v234
	v_lshl_add_u32 v74, v74, 4, s97
	ds_write_b128 v74, v[128:131] offset:8448
	v_lshlrev_b32_e32 v75, 7, v234
	v_lshl_add_u32 v75, v233, 2, v75
	v_add_u32_e32 v75, s97, v75
	v_cmp_le_i32_e64 s[96:97], 0, v77
	v_cmp_le_i32_e64 s[100:101], 1, v77
	s_nop 0
	v_cndmask_b32_e64 v132, 0, v244, s[96:97]
	v_cndmask_b32_e64 v133, 0, v245, s[100:101]
	v_cmp_le_i32_e64 s[96:97], 2, v77
	v_cmp_le_i32_e64 s[100:101], 3, v77
	s_nop 0
	v_cndmask_b32_e64 v134, 0, v246, s[96:97]
	v_cndmask_b32_e64 v135, 0, v247, s[100:101]
	s_mov_b64 exec, 0x00ff00ff
	ds_write_b32 v75, v132 offset:9472
	ds_write_b32 v75, v133 offset:9504
	ds_write_b32 v75, v134 offset:9536
	ds_write_b32 v75, v135 offset:9568
	s_mov_b64 exec, -1
	s_setprio 0
	s_branch .LBB0_655
	s_nop 0
	s_nop 0
	s_nop 0
	s_nop 0
	s_nop 0
	s_nop 0
	s_nop 0
	s_nop 0
	s_nop 0
	s_nop 0
	s_nop 0
	s_nop 0
	s_nop 0
	s_nop 0
